# fused final norm: row-sum reductions batched (16 bpermutes per tile instead of 32 serialized rounds), poll sleep shortened
# baseline (speedup 1.0000x reference)
.Lfz_p11_spin:
	global_load_dword v132, v213, s[90:91] sc1
	s_waitcnt vmcnt(0)
	v_readfirstlane_b32 vcc_lo, v132
	s_cmp_ge_u32 vcc_lo, 16
	s_cbranch_scc1 .Lfz_p11_met
	s_sleep 1
	s_sub_u32 s32, s32, 1
	s_cmp_lg_u32 s32, 0
	s_cbranch_scc1 .Lfz_p11_spin
.Lfz_p11_met:
	buffer_inv sc1
	s_add_u32 s100, s96, 0x5500000
	s_addc_u32 s101, s97, 0
	global_load_dwordx2 v[160:161], v210, s[100:101]
	global_load_dwordx2 v[162:163], v210, s[100:101] offset:512
	s_add_u32 s100, s100, 0x400
	s_addc_u32 s101, s101, 0
	global_load_dwordx2 v[164:165], v210, s[100:101]
	global_load_dwordx2 v[166:167], v210, s[100:101] offset:512
	s_add_u32 s100, s100, 0x400
	s_addc_u32 s101, s101, 0
	global_load_dwordx2 v[168:169], v210, s[100:101]
	global_load_dwordx2 v[170:171], v210, s[100:101] offset:512
	s_add_u32 s100, s100, 0x400
	s_addc_u32 s101, s101, 0
	global_load_dwordx2 v[172:173], v210, s[100:101]
	global_load_dwordx2 v[174:175], v210, s[100:101] offset:512
	s_add_u32 s100, s100, 0x1400
	s_addc_u32 s101, s101, 0
	global_load_dwordx2 v[176:177], v210, s[100:101]
	global_load_dwordx2 v[178:179], v210, s[100:101] offset:512
	s_add_u32 s100, s100, 0x400
	s_addc_u32 s101, s101, 0
	global_load_dwordx2 v[180:181], v210, s[100:101]
	global_load_dwordx2 v[182:183], v210, s[100:101] offset:512
	s_add_u32 s100, s100, 0x400
	s_addc_u32 s101, s101, 0
	global_load_dwordx2 v[184:185], v210, s[100:101]
	global_load_dwordx2 v[186:187], v210, s[100:101] offset:512
	s_add_u32 s100, s100, 0x400
	s_addc_u32 s101, s101, 0
	global_load_dwordx2 v[188:189], v210, s[100:101]
	global_load_dwordx2 v[190:191], v210, s[100:101] offset:512
	v_mov_b32_e32 v211, 0x358637bd
	s_waitcnt vmcnt(0)
	v_add_f32_e32 v160, v160, v161
	v_add_f32_e32 v162, v162, v163
	v_add_f32_e32 v164, v164, v165
	v_add_f32_e32 v166, v166, v167
	v_add_f32_e32 v168, v168, v169
	v_add_f32_e32 v170, v170, v171
	v_add_f32_e32 v172, v172, v173
	v_add_f32_e32 v174, v174, v175
	v_add_f32_e32 v176, v176, v177
	v_add_f32_e32 v178, v178, v179
	v_add_f32_e32 v180, v180, v181
	v_add_f32_e32 v182, v182, v183
	v_add_f32_e32 v184, v184, v185
	v_add_f32_e32 v186, v186, v187
	v_add_f32_e32 v188, v188, v189
	v_add_f32_e32 v190, v190, v191
	s_nop 0
	v_add_f32_dpp v160, v160, v160 row_ror:8 row_mask:0xf bank_mask:0xf
	v_add_f32_dpp v162, v162, v162 row_ror:8 row_mask:0xf bank_mask:0xf
	v_add_f32_dpp v164, v164, v164 row_ror:8 row_mask:0xf bank_mask:0xf
	v_add_f32_dpp v166, v166, v166 row_ror:8 row_mask:0xf bank_mask:0xf
	v_add_f32_dpp v168, v168, v168 row_ror:8 row_mask:0xf bank_mask:0xf
	v_add_f32_dpp v170, v170, v170 row_ror:8 row_mask:0xf bank_mask:0xf
	v_add_f32_dpp v172, v172, v172 row_ror:8 row_mask:0xf bank_mask:0xf
	v_add_f32_dpp v174, v174, v174 row_ror:8 row_mask:0xf bank_mask:0xf
	v_add_f32_dpp v176, v176, v176 row_ror:8 row_mask:0xf bank_mask:0xf
	v_add_f32_dpp v178, v178, v178 row_ror:8 row_mask:0xf bank_mask:0xf
	v_add_f32_dpp v180, v180, v180 row_ror:8 row_mask:0xf bank_mask:0xf
	v_add_f32_dpp v182, v182, v182 row_ror:8 row_mask:0xf bank_mask:0xf
	v_add_f32_dpp v184, v184, v184 row_ror:8 row_mask:0xf bank_mask:0xf
	v_add_f32_dpp v186, v186, v186 row_ror:8 row_mask:0xf bank_mask:0xf
	v_add_f32_dpp v188, v188, v188 row_ror:8 row_mask:0xf bank_mask:0xf
	v_add_f32_dpp v190, v190, v190 row_ror:8 row_mask:0xf bank_mask:0xf
	v_cmp_gt_u32_e64 s[98:99], 8, v212
	s_nop 1
	v_cndmask_b32_e64 v160, v162, v160, s[98:99]
	v_cndmask_b32_e64 v164, v166, v164, s[98:99]
	v_cndmask_b32_e64 v168, v170, v168, s[98:99]
	v_cndmask_b32_e64 v172, v174, v172, s[98:99]
	v_cndmask_b32_e64 v176, v178, v176, s[98:99]
	v_cndmask_b32_e64 v180, v182, v180, s[98:99]
	v_cndmask_b32_e64 v184, v186, v184, s[98:99]
	v_cndmask_b32_e64 v188, v190, v188, s[98:99]
	s_nop 0
	ds_bpermute_b32 v161, v144, v160
	ds_bpermute_b32 v165, v144, v164
	ds_bpermute_b32 v169, v144, v168
	ds_bpermute_b32 v173, v144, v172
	ds_bpermute_b32 v177, v144, v176
	ds_bpermute_b32 v181, v144, v180
	ds_bpermute_b32 v185, v144, v184
	ds_bpermute_b32 v189, v144, v188
	s_waitcnt lgkmcnt(7)
	v_add_f32_e32 v160, v160, v161
	s_waitcnt lgkmcnt(6)
	v_add_f32_e32 v164, v164, v165
	s_waitcnt lgkmcnt(5)
	v_add_f32_e32 v168, v168, v169
	s_waitcnt lgkmcnt(4)
	v_add_f32_e32 v172, v172, v173
	s_waitcnt lgkmcnt(3)
	v_add_f32_e32 v176, v176, v177
	s_waitcnt lgkmcnt(2)
	v_add_f32_e32 v180, v180, v181
	s_waitcnt lgkmcnt(1)
	v_add_f32_e32 v184, v184, v185
	s_waitcnt lgkmcnt(0)
	v_add_f32_e32 v188, v188, v189
	s_nop 0
	ds_bpermute_b32 v161, v145, v160
	ds_bpermute_b32 v165, v145, v164
	ds_bpermute_b32 v169, v145, v168
	ds_bpermute_b32 v173, v145, v172
	ds_bpermute_b32 v177, v145, v176
	ds_bpermute_b32 v181, v145, v180
	ds_bpermute_b32 v185, v145, v184
	ds_bpermute_b32 v189, v145, v188
	s_waitcnt lgkmcnt(7)
	v_add_f32_e32 v160, v160, v161
	s_waitcnt lgkmcnt(6)
	v_add_f32_e32 v164, v164, v165
	s_waitcnt lgkmcnt(5)
	v_add_f32_e32 v168, v168, v169
	s_waitcnt lgkmcnt(4)
	v_add_f32_e32 v172, v172, v173
	s_waitcnt lgkmcnt(3)
	v_add_f32_e32 v176, v176, v177
	s_waitcnt lgkmcnt(2)
	v_add_f32_e32 v180, v180, v181
	s_waitcnt lgkmcnt(1)
	v_add_f32_e32 v184, v184, v185
	s_waitcnt lgkmcnt(0)
	v_add_f32_e32 v188, v188, v189
	s_mov_b32 vcc_lo, 0x3a800000
	v_fma_f32 v160, v160, vcc_lo, v211
	v_fma_f32 v164, v164, vcc_lo, v211
	v_fma_f32 v168, v168, vcc_lo, v211
	v_fma_f32 v172, v172, vcc_lo, v211
	v_fma_f32 v176, v176, vcc_lo, v211
	v_fma_f32 v180, v180, vcc_lo, v211
	v_fma_f32 v184, v184, vcc_lo, v211
	v_fma_f32 v188, v188, vcc_lo, v211
	v_rsq_f32_e32 v160, v160
	v_rsq_f32_e32 v164, v164
	v_rsq_f32_e32 v168, v168
	v_rsq_f32_e32 v172, v172
	v_rsq_f32_e32 v176, v176
	v_rsq_f32_e32 v180, v180
	v_rsq_f32_e32 v184, v184
	v_rsq_f32_e32 v188, v188
	s_nop 1
	v_mov_b32_dpp v161, v160 row_ror:8 row_mask:0xf bank_mask:0xf
	v_mov_b32_dpp v165, v164 row_ror:8 row_mask:0xf bank_mask:0xf
	v_mov_b32_dpp v169, v168 row_ror:8 row_mask:0xf bank_mask:0xf
	v_mov_b32_dpp v173, v172 row_ror:8 row_mask:0xf bank_mask:0xf
	v_mov_b32_dpp v177, v176 row_ror:8 row_mask:0xf bank_mask:0xf
	v_mov_b32_dpp v181, v180 row_ror:8 row_mask:0xf bank_mask:0xf
	v_mov_b32_dpp v185, v184 row_ror:8 row_mask:0xf bank_mask:0xf
	v_mov_b32_dpp v189, v188 row_ror:8 row_mask:0xf bank_mask:0xf
	v_cndmask_b32_e64 v162, v160, v161, s[98:99]
	v_cndmask_b32_e64 v160, v161, v160, s[98:99]
	v_cndmask_b32_e64 v166, v164, v165, s[98:99]
	v_cndmask_b32_e64 v164, v165, v164, s[98:99]
	v_cndmask_b32_e64 v170, v168, v169, s[98:99]
	v_cndmask_b32_e64 v168, v169, v168, s[98:99]
	v_cndmask_b32_e64 v174, v172, v173, s[98:99]
	v_cndmask_b32_e64 v172, v173, v172, s[98:99]
	v_cndmask_b32_e64 v178, v176, v177, s[98:99]
	v_cndmask_b32_e64 v176, v177, v176, s[98:99]
	v_cndmask_b32_e64 v182, v180, v181, s[98:99]
	v_cndmask_b32_e64 v180, v181, v180, s[98:99]
	v_cndmask_b32_e64 v186, v184, v185, s[98:99]
	v_cndmask_b32_e64 v184, v185, v184, s[98:99]
	v_cndmask_b32_e64 v190, v188, v189, s[98:99]
	v_cndmask_b32_e64 v188, v189, v188, s[98:99]
	v_mul_f32_e32 v124, v124, v160
	v_mul_f32_e32 v125, v125, v160
	v_mul_f32_e32 v126, v126, v160
	v_mul_f32_e32 v127, v127, v160
	v_mul_f32_e32 v124, v124, v192
	v_mul_f32_e32 v125, v125, v193
	v_mul_f32_e32 v126, v126, v194
	v_mul_f32_e32 v127, v127, v195
	global_store_dwordx4 v148, v[124:127], s[88:89]
	v_mul_f32_e32 v120, v120, v162
	v_mul_f32_e32 v121, v121, v162
	v_mul_f32_e32 v122, v122, v162
	v_mul_f32_e32 v123, v123, v162
	v_mul_f32_e32 v120, v120, v192
	v_mul_f32_e32 v121, v121, v193
	v_mul_f32_e32 v122, v122, v194
	v_mul_f32_e32 v123, v123, v195
	global_store_dwordx4 v149, v[120:123], s[88:89]
	v_mul_f32_e32 v116, v116, v160
	v_mul_f32_e32 v117, v117, v160
	v_mul_f32_e32 v118, v118, v160
	v_mul_f32_e32 v119, v119, v160
	v_mul_f32_e32 v116, v116, v196
	v_mul_f32_e32 v117, v117, v197
	v_mul_f32_e32 v118, v118, v198
	v_mul_f32_e32 v119, v119, v199
	global_store_dwordx4 v148, v[116:119], s[88:89] offset:512
	v_mul_f32_e32 v112, v112, v162
	v_mul_f32_e32 v113, v113, v162
	v_mul_f32_e32 v114, v114, v162
	v_mul_f32_e32 v115, v115, v162
	v_mul_f32_e32 v112, v112, v196
	v_mul_f32_e32 v113, v113, v197
	v_mul_f32_e32 v114, v114, v198
	v_mul_f32_e32 v115, v115, v199
	global_store_dwordx4 v149, v[112:115], s[88:89] offset:512
	s_add_u32 s88, s88, 0x10000
	s_addc_u32 s89, s89, 0
	v_mul_f32_e32 v108, v108, v164
	v_mul_f32_e32 v109, v109, v164
	v_mul_f32_e32 v110, v110, v164
	v_mul_f32_e32 v111, v111, v164
	v_mul_f32_e32 v108, v108, v192
	v_mul_f32_e32 v109, v109, v193
	v_mul_f32_e32 v110, v110, v194
	v_mul_f32_e32 v111, v111, v195
	global_store_dwordx4 v148, v[108:111], s[88:89]
	v_mul_f32_e32 v104, v104, v166
	v_mul_f32_e32 v105, v105, v166
	v_mul_f32_e32 v106, v106, v166
	v_mul_f32_e32 v107, v107, v166
	v_mul_f32_e32 v104, v104, v192
	v_mul_f32_e32 v105, v105, v193
	v_mul_f32_e32 v106, v106, v194
	v_mul_f32_e32 v107, v107, v195
	global_store_dwordx4 v149, v[104:107], s[88:89]
	v_mul_f32_e32 v100, v100, v164
	v_mul_f32_e32 v101, v101, v164
	v_mul_f32_e32 v102, v102, v164
	v_mul_f32_e32 v103, v103, v164
	v_mul_f32_e32 v100, v100, v196
	v_mul_f32_e32 v101, v101, v197
	v_mul_f32_e32 v102, v102, v198
	v_mul_f32_e32 v103, v103, v199
	global_store_dwordx4 v148, v[100:103], s[88:89] offset:512
	v_mul_f32_e32 v96, v96, v166
	v_mul_f32_e32 v97, v97, v166
	v_mul_f32_e32 v98, v98, v166
	v_mul_f32_e32 v99, v99, v166
	v_mul_f32_e32 v96, v96, v196
	v_mul_f32_e32 v97, v97, v197
	v_mul_f32_e32 v98, v98, v198
	v_mul_f32_e32 v99, v99, v199
	global_store_dwordx4 v149, v[96:99], s[88:89] offset:512
	s_add_u32 s88, s88, 0x10000
	s_addc_u32 s89, s89, 0
	v_mul_f32_e32 v92, v92, v168
	v_mul_f32_e32 v93, v93, v168
	v_mul_f32_e32 v94, v94, v168
	v_mul_f32_e32 v95, v95, v168
	v_mul_f32_e32 v92, v92, v192
	v_mul_f32_e32 v93, v93, v193
	v_mul_f32_e32 v94, v94, v194
	v_mul_f32_e32 v95, v95, v195
	global_store_dwordx4 v148, v[92:95], s[88:89]
	v_mul_f32_e32 v88, v88, v170
	v_mul_f32_e32 v89, v89, v170
	v_mul_f32_e32 v90, v90, v170
	v_mul_f32_e32 v91, v91, v170
	v_mul_f32_e32 v88, v88, v192
	v_mul_f32_e32 v89, v89, v193
	v_mul_f32_e32 v90, v90, v194
	v_mul_f32_e32 v91, v91, v195
	global_store_dwordx4 v149, v[88:91], s[88:89]
	v_mul_f32_e32 v84, v84, v168
	v_mul_f32_e32 v85, v85, v168
	v_mul_f32_e32 v86, v86, v168
	v_mul_f32_e32 v87, v87, v168
	v_mul_f32_e32 v84, v84, v196
	v_mul_f32_e32 v85, v85, v197
	v_mul_f32_e32 v86, v86, v198
	v_mul_f32_e32 v87, v87, v199
	global_store_dwordx4 v148, v[84:87], s[88:89] offset:512
	v_mul_f32_e32 v80, v80, v170
	v_mul_f32_e32 v81, v81, v170
	v_mul_f32_e32 v82, v82, v170
	v_mul_f32_e32 v83, v83, v170
	v_mul_f32_e32 v80, v80, v196
	v_mul_f32_e32 v81, v81, v197
	v_mul_f32_e32 v82, v82, v198
	v_mul_f32_e32 v83, v83, v199
	global_store_dwordx4 v149, v[80:83], s[88:89] offset:512
	s_add_u32 s88, s88, 0x10000
	s_addc_u32 s89, s89, 0
	v_mul_f32_e32 v76, v76, v172
	v_mul_f32_e32 v77, v77, v172
	v_mul_f32_e32 v78, v78, v172
	v_mul_f32_e32 v79, v79, v172
	v_mul_f32_e32 v76, v76, v192
	v_mul_f32_e32 v77, v77, v193
	v_mul_f32_e32 v78, v78, v194
	v_mul_f32_e32 v79, v79, v195
	global_store_dwordx4 v148, v[76:79], s[88:89]
	v_mul_f32_e32 v72, v72, v174
	v_mul_f32_e32 v73, v73, v174
	v_mul_f32_e32 v74, v74, v174
	v_mul_f32_e32 v75, v75, v174
	v_mul_f32_e32 v72, v72, v192
	v_mul_f32_e32 v73, v73, v193
	v_mul_f32_e32 v74, v74, v194
	v_mul_f32_e32 v75, v75, v195
	global_store_dwordx4 v149, v[72:75], s[88:89]
	v_mul_f32_e32 v68, v68, v172
	v_mul_f32_e32 v69, v69, v172
	v_mul_f32_e32 v70, v70, v172
	v_mul_f32_e32 v71, v71, v172
	v_mul_f32_e32 v68, v68, v196
	v_mul_f32_e32 v69, v69, v197
	v_mul_f32_e32 v70, v70, v198
	v_mul_f32_e32 v71, v71, v199
	global_store_dwordx4 v148, v[68:71], s[88:89] offset:512
	v_mul_f32_e32 v64, v64, v174
	v_mul_f32_e32 v65, v65, v174
	v_mul_f32_e32 v66, v66, v174
	v_mul_f32_e32 v67, v67, v174
	v_mul_f32_e32 v64, v64, v196
	v_mul_f32_e32 v65, v65, v197
	v_mul_f32_e32 v66, v66, v198
	v_mul_f32_e32 v67, v67, v199
	global_store_dwordx4 v149, v[64:67], s[88:89] offset:512
	s_add_u32 s88, s88, 0x50000
	s_addc_u32 s89, s89, 0
	v_mul_f32_e32 v60, v60, v176
	v_mul_f32_e32 v61, v61, v176
	v_mul_f32_e32 v62, v62, v176
	v_mul_f32_e32 v63, v63, v176
	v_mul_f32_e32 v60, v60, v192
	v_mul_f32_e32 v61, v61, v193
	v_mul_f32_e32 v62, v62, v194
	v_mul_f32_e32 v63, v63, v195
	global_store_dwordx4 v148, v[60:63], s[88:89]
	v_mul_f32_e32 v56, v56, v178
	v_mul_f32_e32 v57, v57, v178
	v_mul_f32_e32 v58, v58, v178
	v_mul_f32_e32 v59, v59, v178
	v_mul_f32_e32 v56, v56, v192
	v_mul_f32_e32 v57, v57, v193
	v_mul_f32_e32 v58, v58, v194
	v_mul_f32_e32 v59, v59, v195
	global_store_dwordx4 v149, v[56:59], s[88:89]
	v_mul_f32_e32 v52, v52, v176
	v_mul_f32_e32 v53, v53, v176
	v_mul_f32_e32 v54, v54, v176
	v_mul_f32_e32 v55, v55, v176
	v_mul_f32_e32 v52, v52, v196
	v_mul_f32_e32 v53, v53, v197
	v_mul_f32_e32 v54, v54, v198
	v_mul_f32_e32 v55, v55, v199
	global_store_dwordx4 v148, v[52:55], s[88:89] offset:512
	v_mul_f32_e32 v48, v48, v178
	v_mul_f32_e32 v49, v49, v178
	v_mul_f32_e32 v50, v50, v178
	v_mul_f32_e32 v51, v51, v178
	v_mul_f32_e32 v48, v48, v196
	v_mul_f32_e32 v49, v49, v197
	v_mul_f32_e32 v50, v50, v198
	v_mul_f32_e32 v51, v51, v199
	global_store_dwordx4 v149, v[48:51], s[88:89] offset:512
	s_add_u32 s88, s88, 0x10000
	s_addc_u32 s89, s89, 0
	v_mul_f32_e32 v44, v44, v180
	v_mul_f32_e32 v45, v45, v180
	v_mul_f32_e32 v46, v46, v180
	v_mul_f32_e32 v47, v47, v180
	v_mul_f32_e32 v44, v44, v192
	v_mul_f32_e32 v45, v45, v193
	v_mul_f32_e32 v46, v46, v194
	v_mul_f32_e32 v47, v47, v195
	global_store_dwordx4 v148, v[44:47], s[88:89]
	v_mul_f32_e32 v40, v40, v182
	v_mul_f32_e32 v41, v41, v182
	v_mul_f32_e32 v42, v42, v182
	v_mul_f32_e32 v43, v43, v182
	v_mul_f32_e32 v40, v40, v192
	v_mul_f32_e32 v41, v41, v193
	v_mul_f32_e32 v42, v42, v194
	v_mul_f32_e32 v43, v43, v195
	global_store_dwordx4 v149, v[40:43], s[88:89]
	v_mul_f32_e32 v36, v36, v180
	v_mul_f32_e32 v37, v37, v180
	v_mul_f32_e32 v38, v38, v180
	v_mul_f32_e32 v39, v39, v180
	v_mul_f32_e32 v36, v36, v196
	v_mul_f32_e32 v37, v37, v197
	v_mul_f32_e32 v38, v38, v198
	v_mul_f32_e32 v39, v39, v199
	global_store_dwordx4 v148, v[36:39], s[88:89] offset:512
	v_mul_f32_e32 v32, v32, v182
	v_mul_f32_e32 v33, v33, v182
	v_mul_f32_e32 v34, v34, v182
	v_mul_f32_e32 v35, v35, v182
	v_mul_f32_e32 v32, v32, v196
	v_mul_f32_e32 v33, v33, v197
	v_mul_f32_e32 v34, v34, v198
	v_mul_f32_e32 v35, v35, v199
	global_store_dwordx4 v149, v[32:35], s[88:89] offset:512
	s_add_u32 s88, s88, 0x10000
	s_addc_u32 s89, s89, 0
	v_mul_f32_e32 v28, v28, v184
	v_mul_f32_e32 v29, v29, v184
	v_mul_f32_e32 v30, v30, v184
	v_mul_f32_e32 v31, v31, v184
	v_mul_f32_e32 v28, v28, v192
	v_mul_f32_e32 v29, v29, v193
	v_mul_f32_e32 v30, v30, v194
	v_mul_f32_e32 v31, v31, v195
	global_store_dwordx4 v148, v[28:31], s[88:89]
	v_mul_f32_e32 v24, v24, v186
	v_mul_f32_e32 v25, v25, v186
	v_mul_f32_e32 v26, v26, v186
	v_mul_f32_e32 v27, v27, v186
	v_mul_f32_e32 v24, v24, v192
	v_mul_f32_e32 v25, v25, v193
	v_mul_f32_e32 v26, v26, v194
	v_mul_f32_e32 v27, v27, v195
	global_store_dwordx4 v149, v[24:27], s[88:89]
	v_mul_f32_e32 v20, v20, v184
	v_mul_f32_e32 v21, v21, v184
	v_mul_f32_e32 v22, v22, v184
	v_mul_f32_e32 v23, v23, v184
	v_mul_f32_e32 v20, v20, v196
	v_mul_f32_e32 v21, v21, v197
	v_mul_f32_e32 v22, v22, v198
	v_mul_f32_e32 v23, v23, v199
	global_store_dwordx4 v148, v[20:23], s[88:89] offset:512
	v_mul_f32_e32 v16, v16, v186
	v_mul_f32_e32 v17, v17, v186
	v_mul_f32_e32 v18, v18, v186
	v_mul_f32_e32 v19, v19, v186
	v_mul_f32_e32 v16, v16, v196
	v_mul_f32_e32 v17, v17, v197
	v_mul_f32_e32 v18, v18, v198
	v_mul_f32_e32 v19, v19, v199
	global_store_dwordx4 v149, v[16:19], s[88:89] offset:512
	s_add_u32 s88, s88, 0x10000
	s_addc_u32 s89, s89, 0
	v_mul_f32_e32 v12, v12, v188
	v_mul_f32_e32 v13, v13, v188
	v_mul_f32_e32 v14, v14, v188
	v_mul_f32_e32 v15, v15, v188
	v_mul_f32_e32 v12, v12, v192
	v_mul_f32_e32 v13, v13, v193
	v_mul_f32_e32 v14, v14, v194
	v_mul_f32_e32 v15, v15, v195
	global_store_dwordx4 v148, v[12:15], s[88:89]
	v_mul_f32_e32 v8, v8, v190
	v_mul_f32_e32 v9, v9, v190
	v_mul_f32_e32 v10, v10, v190
	v_mul_f32_e32 v11, v11, v190
	v_mul_f32_e32 v8, v8, v192
	v_mul_f32_e32 v9, v9, v193
	v_mul_f32_e32 v10, v10, v194
	v_mul_f32_e32 v11, v11, v195
	global_store_dwordx4 v149, v[8:11], s[88:89]
	v_mul_f32_e32 v4, v4, v188
	v_mul_f32_e32 v5, v5, v188
	v_mul_f32_e32 v6, v6, v188
	v_mul_f32_e32 v7, v7, v188
	v_mul_f32_e32 v4, v4, v196
	v_mul_f32_e32 v5, v5, v197
	v_mul_f32_e32 v6, v6, v198
	v_mul_f32_e32 v7, v7, v199
	global_store_dwordx4 v148, v[4:7], s[88:89] offset:512
	v_mul_f32_e32 v0, v0, v190
	v_mul_f32_e32 v1, v1, v190
	v_mul_f32_e32 v2, v2, v190
	v_mul_f32_e32 v3, v3, v190
	v_mul_f32_e32 v0, v0, v196
	v_mul_f32_e32 v1, v1, v197
	v_mul_f32_e32 v2, v2, v198
	v_mul_f32_e32 v3, v3, v199
	global_store_dwordx4 v149, v[0:3], s[88:89] offset:512
	s_and_b64 vcc, exec, s[8:9]
	s_mov_b64 s[8:9], -1
	s_cbranch_vccnz .LBB0_1477
	s_andn2_b64 vcc, exec, s[14:15]
	s_cbranch_vccnz .LBB0_1476
	s_barrier
	s_branch .LBB0_1476
